# transpose loops: counted vmcnt(1) at loop top (previous tile store stays in flight), vmcnt(0) peeled before loop entry
# baseline (speedup 1.0000x reference)
.LBB0_17:
	s_load_dwordx16 s[4:19], s[0:1], 0x0
	s_add_u32 s3, s42, 0x9800000
	s_addc_u32 s28, s43, 0
	s_cmpk_lt_i32 s85, 0x200
	s_cselect_b64 s[0:1], -1, 0
	s_waitcnt lgkmcnt(0)
	v_writelane_b32 v252, s4, 4
	v_mov_b32_e32 v10, v170
	s_cmpk_gt_i32 s85, 0x1ff
	v_writelane_b32 v252, s5, 5
	v_writelane_b32 v252, s6, 6
	v_writelane_b32 v252, s7, 7
	v_writelane_b32 v252, s8, 8
	v_writelane_b32 v252, s9, 9
	v_writelane_b32 v252, s10, 10
	v_writelane_b32 v252, s11, 11
	v_writelane_b32 v252, s12, 12
	v_writelane_b32 v252, s13, 13
	v_writelane_b32 v252, s14, 14
	v_writelane_b32 v252, s15, 15
	v_writelane_b32 v252, s16, 16
	v_writelane_b32 v252, s17, 17
	v_writelane_b32 v252, s18, 18
	v_writelane_b32 v252, s19, 19
	v_writelane_b32 v252, s0, 20
	s_nop 1
	v_writelane_b32 v252, s1, 21
	s_cbranch_scc1 .LBB0_22
	s_ashr_i32 s0, s85, 31
	s_lshr_b32 s0, s0, 26
	s_add_i32 s1, s85, s0
	s_ashr_i32 s0, s1, 6
	s_and_b32 s1, s1, 0xffc0
	s_sub_i32 s1, s85, s1
	s_bfe_i32 s2, s1, 0x80000
	s_bfe_u32 s2, s2, 0x3000c
	s_add_i32 s2, s1, s2
	s_bfe_i32 s4, s2, 0x80000
	s_and_b32 s2, s2, 0xf8
	s_sub_i32 s1, s1, s2
	s_sext_i32_i8 s2, s1
	s_ashr_i32 s1, s0, 31
	v_readlane_b32 s8, v252, 4
	s_lshl_b64 s[0:1], s[0:1], 20
	v_readlane_b32 s12, v252, 8
	s_sext_i32_i16 s4, s4
	v_readlane_b32 s13, v252, 9
	s_add_u32 s5, s12, s0
	s_addc_u32 s6, s13, s1
	s_lshl_b32 s0, s4, 3
	s_and_b32 s4, s0, 0xffffffc0
	s_lshl_b32 s0, s2, 6
	s_ashr_i32 s1, s0, 31
	s_lshl_b64 s[0:1], s[0:1], 2
	v_lshlrev_b32_e32 v0, 2, v10
	v_ashrrev_i32_e32 v12, 4, v10
	s_add_u32 s0, s5, s0
	v_and_b32_e32 v18, 60, v0
	v_add_u32_e32 v2, s4, v12
	s_addc_u32 s1, s6, s1
	v_mov_b32_e32 v9, 0
	v_lshlrev_b32_e32 v8, 2, v18
	v_ashrrev_i32_e32 v3, 31, v2
	v_lshl_add_u64 v[0:1], s[0:1], 0, v[8:9]
	v_lshlrev_b64 v[2:3], 11, v[2:3]
	v_lshl_add_u64 v[14:15], v[0:1], 0, v[2:3]
	v_add_u32_e32 v2, 0x200, v10
	v_ashrrev_i32_e32 v13, 4, v2
	v_add_u32_e32 v2, s4, v13
	v_ashrrev_i32_e32 v3, 31, v2
	v_lshlrev_b64 v[2:3], 11, v[2:3]
	v_lshl_add_u64 v[16:17], v[0:1], 0, v[2:3]
	global_load_dwordx4 v[0:3], v[14:15], off nt
	global_load_dwordx4 v[4:7], v[16:17], off nt
	v_add_u32_e32 v11, 0, v8
	v_lshlrev_b32_e32 v8, 3, v10
	v_ashrrev_i32_e32 v14, 3, v10
	v_and_b32_e32 v8, 56, v8
	s_movk_i32 s0, 0x104
	v_mul_u32_u24_e32 v10, 0x104, v8
	v_lshlrev_b32_e32 v15, 2, v14
	v_add3_u32 v15, 0, v10, v15
	v_mul_lo_u32 v10, v12, s0
	v_mul_lo_u32 v17, v13, s0
	v_add_u32_e32 v16, v11, v10
	v_add_u32_e32 v17, v11, v17
	v_lshlrev_b32_e32 v10, 2, v18
	v_lshlrev_b32_e32 v8, 1, v8
	s_mov_b32 s4, s85
	v_readlane_b32 s9, v252, 5
	v_readlane_b32 s10, v252, 6
	v_readlane_b32 s11, v252, 7
	v_readlane_b32 s14, v252, 10
	v_readlane_b32 s15, v252, 11
	v_readlane_b32 s16, v252, 12
	v_readlane_b32 s17, v252, 13
	v_readlane_b32 s18, v252, 14
	v_readlane_b32 s19, v252, 15
	v_readlane_b32 s20, v252, 16
	v_readlane_b32 s21, v252, 17
	v_readlane_b32 s22, v252, 18
	v_readlane_b32 s23, v252, 19
	s_waitcnt vmcnt(0)
	s_branch .LBB0_20

.LBB0_20:
	s_add_i32 s2, s4, s92
	s_cmpk_gt_i32 s2, 0x1ff
	s_cselect_b64 s[0:1], -1, 0
	s_and_b64 vcc, exec, s[0:1]
	s_waitcnt vmcnt(1)
	ds_write2_b32 v16, v0, v1 offset1:1
	ds_write2_b32 v16, v2, v3 offset0:2 offset1:3
	s_waitcnt vmcnt(1)
	ds_write2_b32 v17, v4, v5 offset1:1
	ds_write2_b32 v17, v6, v7 offset0:2 offset1:3
	s_cbranch_vccnz .LBB0_19
	s_ashr_i32 s5, s2, 31
	s_lshr_b32 s5, s5, 26
	s_add_i32 s5, s2, s5
	s_ashr_i32 s6, s5, 6
	s_and_b32 s5, s5, 0xffc0
	s_sub_i32 s5, s2, s5
	s_bfe_i32 s7, s5, 0x80000
	s_bfe_u32 s7, s7, 0x3000c
	s_add_i32 s7, s5, s7
	s_bfe_i32 s8, s7, 0x80000
	s_and_b32 s7, s7, 0xf8
	s_sub_i32 s5, s5, s7
	s_ashr_i32 s7, s6, 31
	v_readlane_b32 s12, v252, 4
	s_lshl_b64 s[6:7], s[6:7], 20
	v_readlane_b32 s16, v252, 8
	s_sext_i32_i16 s8, s8
	v_readlane_b32 s17, v252, 9
	s_add_u32 s9, s16, s6
	s_sext_i32_i8 s5, s5
	s_addc_u32 s10, s17, s7
	s_lshl_b32 s6, s8, 3
	s_and_b32 s8, s6, 0xffffffc0
	s_lshl_b32 s6, s5, 6
	s_ashr_i32 s7, s6, 31
	s_lshl_b64 s[6:7], s[6:7], 2
	s_add_u32 s6, s9, s6
	v_add_u32_e32 v2, s8, v12
	s_addc_u32 s7, s10, s7
	v_mov_b32_e32 v11, v9
	v_ashrrev_i32_e32 v3, 31, v2
	v_lshl_add_u64 v[0:1], s[6:7], 0, v[10:11]
	v_lshlrev_b64 v[2:3], 11, v[2:3]
	v_lshl_add_u64 v[18:19], v[0:1], 0, v[2:3]
	v_add_u32_e32 v2, s8, v13
	v_ashrrev_i32_e32 v3, 31, v2
	v_lshlrev_b64 v[2:3], 11, v[2:3]
	v_lshl_add_u64 v[20:21], v[0:1], 0, v[2:3]
	global_load_dwordx4 v[0:3], v[18:19], off nt
	global_load_dwordx4 v[4:7], v[20:21], off nt
	v_readlane_b32 s13, v252, 5
	v_readlane_b32 s14, v252, 6
	v_readlane_b32 s15, v252, 7
	v_readlane_b32 s18, v252, 10
	v_readlane_b32 s19, v252, 11
	v_readlane_b32 s20, v252, 12
	v_readlane_b32 s21, v252, 13
	v_readlane_b32 s22, v252, 14
	v_readlane_b32 s23, v252, 15
	v_readlane_b32 s24, v252, 16
	v_readlane_b32 s25, v252, 17
	v_readlane_b32 s26, v252, 18
	v_readlane_b32 s27, v252, 19
	s_branch .LBB0_19

.LBB0_97:
	s_cmpk_lt_i32 s85, 0x400
	v_mov_b32_e32 v10, v170
	s_cselect_b64 s[0:1], -1, 0
	s_cmpk_gt_i32 s85, 0x3ff
	s_cbranch_scc1 .LBB0_102
	s_add_u32 s3, s42, 0x8400000
	s_addc_u32 s6, s43, 0
	s_ashr_i32 s4, s85, 31
	s_lshr_b32 s4, s4, 23
	s_add_i32 s5, s85, s4
	s_ashr_i32 s4, s5, 9
	s_and_b32 s5, s5, 0xfe00
	s_sub_i32 s5, s85, s5
	s_sext_i32_i16 s7, s5
	s_bfe_u32 s7, s7, 0x5001a
	s_add_i32 s7, s5, s7
	s_sext_i32_i16 s8, s7
	s_and_b32 s7, s7, 0xffe0
	s_sub_i32 s5, s5, s7
	s_sext_i32_i16 s7, s5
	s_ashr_i32 s5, s4, 31
	v_readlane_b32 s12, v252, 4
	s_lshl_b64 s[4:5], s[4:5], 24
	v_readlane_b32 s14, v252, 6
	v_readlane_b32 s15, v252, 7
	s_add_u32 s9, s14, s4
	s_addc_u32 s12, s15, s5
	s_lshl_b32 s4, s8, 1
	s_and_b32 s8, s4, 0xffffffc0
	s_lshl_b32 s4, s7, 6
	s_ashr_i32 s5, s4, 31
	s_lshl_b64 s[4:5], s[4:5], 2
	v_lshlrev_b32_e32 v0, 2, v10
	s_add_u32 s4, s9, s4
	v_and_b32_e32 v18, 60, v0
	v_ashrrev_i32_e32 v12, 4, v10
	s_addc_u32 s5, s12, s5
	v_mov_b32_e32 v9, 0
	v_lshlrev_b32_e32 v8, 2, v18
	v_add_u32_e32 v2, s8, v12
	v_lshl_add_u64 v[0:1], s[4:5], 0, v[8:9]
	s_mov_b64 s[4:5], 0x2000
	v_ashrrev_i32_e32 v3, 31, v2
	v_lshl_add_u64 v[0:1], v[0:1], 0, s[4:5]
	v_lshlrev_b64 v[2:3], 14, v[2:3]
	v_lshl_add_u64 v[14:15], v[0:1], 0, v[2:3]
	v_add_u32_e32 v2, 0x200, v10
	v_ashrrev_i32_e32 v13, 4, v2
	v_add_u32_e32 v2, s8, v13
	v_ashrrev_i32_e32 v3, 31, v2
	v_lshlrev_b64 v[2:3], 14, v[2:3]
	v_lshl_add_u64 v[16:17], v[0:1], 0, v[2:3]
	global_load_dwordx4 v[0:3], v[14:15], off nt
	global_load_dwordx4 v[4:7], v[16:17], off nt
	v_add_u32_e32 v11, 0, v8
	v_lshlrev_b32_e32 v8, 3, v10
	v_ashrrev_i32_e32 v14, 3, v10
	v_and_b32_e32 v8, 56, v8
	s_movk_i32 s4, 0x104
	v_mul_u32_u24_e32 v10, 0x104, v8
	v_lshlrev_b32_e32 v15, 2, v14
	s_add_u32 s7, s14, 0x2000
	v_add3_u32 v15, 0, v10, v15
	v_mul_lo_u32 v10, v12, s4
	v_mul_lo_u32 v17, v13, s4
	s_addc_u32 s8, s15, 0
	v_add_u32_e32 v16, v11, v10
	v_add_u32_e32 v17, v11, v17
	v_lshlrev_b32_e32 v10, 2, v18
	v_lshlrev_b32_e32 v8, 1, v8
	s_mov_b32 s12, s85
	v_readlane_b32 s13, v252, 5
	v_readlane_b32 s16, v252, 8
	v_readlane_b32 s17, v252, 9
	v_readlane_b32 s18, v252, 10
	v_readlane_b32 s19, v252, 11
	v_readlane_b32 s20, v252, 12
	v_readlane_b32 s21, v252, 13
	v_readlane_b32 s22, v252, 14
	v_readlane_b32 s23, v252, 15
	v_readlane_b32 s24, v252, 16
	v_readlane_b32 s25, v252, 17
	v_readlane_b32 s26, v252, 18
	v_readlane_b32 s27, v252, 19
	s_waitcnt vmcnt(0)
	s_branch .LBB0_100

.LBB0_100:
	s_add_i32 s9, s12, s92
	s_cmpk_gt_i32 s9, 0x3ff
	s_cselect_b64 s[4:5], -1, 0
	s_and_b64 vcc, exec, s[4:5]
	s_waitcnt vmcnt(1)
	ds_write2_b32 v16, v0, v1 offset1:1
	ds_write2_b32 v16, v2, v3 offset0:2 offset1:3
	ds_write2_b32 v17, v4, v5 offset1:1
	ds_write2_b32 v17, v6, v7 offset0:2 offset1:3
	s_cbranch_vccnz .LBB0_99
	s_ashr_i32 s13, s9, 31
	s_lshr_b32 s13, s13, 23
	s_add_i32 s13, s9, s13
	s_ashr_i32 s14, s13, 9
	s_and_b32 s13, s13, 0xfe00
	s_sub_i32 s13, s9, s13
	s_sext_i32_i16 s15, s13
	s_bfe_u32 s15, s15, 0x5001a
	s_add_i32 s15, s13, s15
	s_sext_i32_i16 s16, s15
	s_and_b32 s15, s15, 0xffe0
	s_sub_i32 s13, s13, s15
	s_ashr_i32 s15, s14, 31
	s_lshl_b64 s[14:15], s[14:15], 24
	s_add_u32 s17, s7, s14
	s_sext_i32_i16 s13, s13
	s_addc_u32 s18, s8, s15
	s_lshl_b32 s14, s16, 1
	s_and_b32 s16, s14, 0xffffffc0
	s_lshl_b32 s14, s13, 6
	s_ashr_i32 s15, s14, 31
	s_lshl_b64 s[14:15], s[14:15], 2
	s_add_u32 s14, s17, s14
	v_add_u32_e32 v2, s16, v12
	s_addc_u32 s15, s18, s15
	v_mov_b32_e32 v11, v9
	v_ashrrev_i32_e32 v3, 31, v2
	v_lshl_add_u64 v[0:1], s[14:15], 0, v[10:11]
	v_lshlrev_b64 v[2:3], 14, v[2:3]
	v_lshl_add_u64 v[18:19], v[0:1], 0, v[2:3]
	v_add_u32_e32 v2, s16, v13
	v_ashrrev_i32_e32 v3, 31, v2
	v_lshlrev_b64 v[2:3], 14, v[2:3]
	v_lshl_add_u64 v[20:21], v[0:1], 0, v[2:3]
	global_load_dwordx4 v[0:3], v[18:19], off nt
	global_load_dwordx4 v[4:7], v[20:21], off nt
	s_branch .LBB0_99
.LBB0_102:
	s_add_u32 s64, s42, 0x9000000
	s_waitcnt vmcnt(0)
	v_cndmask_b32_e64 v0, 0, 1, s[0:1]
	s_addc_u32 s65, s43, 0
	v_mov_b32_e32 v10, v170
	v_cmp_ne_u32_e64 s[8:9], 1, v0
	s_andn2_b64 vcc, exec, s[0:1]
	s_cbranch_vccnz .LBB0_107
	s_ashr_i32 s0, s85, 31
	s_lshr_b32 s0, s0, 23
	s_add_i32 s1, s85, s0
	s_ashr_i32 s0, s1, 9
	s_and_b32 s1, s1, 0xfe00
	s_sub_i32 s1, s85, s1
	s_sext_i32_i16 s3, s1
	s_bfe_u32 s3, s3, 0x4001b
	s_add_i32 s3, s1, s3
	s_sext_i32_i16 s4, s3
	s_and_b32 s3, s3, 0xfff0
	s_sub_i32 s1, s1, s3
	s_sext_i32_i16 s3, s1
	s_ashr_i32 s1, s0, 31
	v_readlane_b32 s12, v252, 4
	s_lshl_b64 s[0:1], s[0:1], 23
	v_readlane_b32 s20, v252, 12
	v_readlane_b32 s21, v252, 13
	s_add_u32 s5, s20, s0
	s_addc_u32 s6, s21, s1
	s_lshl_b32 s0, s4, 2
	s_and_b32 s4, s0, 0xffffffc0
	s_lshl_b32 s0, s3, 6
	s_ashr_i32 s1, s0, 31
	s_lshl_b64 s[0:1], s[0:1], 2
	v_lshlrev_b32_e32 v0, 2, v10
	v_ashrrev_i32_e32 v12, 4, v10
	s_add_u32 s0, s5, s0
	v_and_b32_e32 v18, 60, v0
	v_add_u32_e32 v2, s4, v12
	s_addc_u32 s1, s6, s1
	v_mov_b32_e32 v9, 0
	v_lshlrev_b32_e32 v8, 2, v18
	v_ashrrev_i32_e32 v3, 31, v2
	v_lshl_add_u64 v[0:1], s[0:1], 0, v[8:9]
	v_lshlrev_b64 v[2:3], 12, v[2:3]
	v_lshl_add_u64 v[14:15], v[0:1], 0, v[2:3]
	v_add_u32_e32 v2, 0x200, v10
	v_ashrrev_i32_e32 v13, 4, v2
	v_add_u32_e32 v2, s4, v13
	v_ashrrev_i32_e32 v3, 31, v2
	v_lshlrev_b64 v[2:3], 12, v[2:3]
	v_lshl_add_u64 v[16:17], v[0:1], 0, v[2:3]
	global_load_dwordx4 v[0:3], v[14:15], off nt
	global_load_dwordx4 v[4:7], v[16:17], off nt
	v_add_u32_e32 v11, 0, v8
	v_lshlrev_b32_e32 v8, 3, v10
	v_ashrrev_i32_e32 v14, 3, v10
	v_and_b32_e32 v8, 56, v8
	s_movk_i32 s0, 0x104
	v_mul_u32_u24_e32 v10, 0x104, v8
	v_lshlrev_b32_e32 v15, 2, v14
	v_add3_u32 v15, 0, v10, v15
	v_mul_lo_u32 v10, v12, s0
	v_mul_lo_u32 v17, v13, s0
	v_add_u32_e32 v16, v11, v10
	v_add_u32_e32 v17, v11, v17
	v_lshlrev_b32_e32 v10, 2, v18
	v_lshlrev_b32_e32 v8, 1, v8
	s_mov_b32 s4, s85
	v_readlane_b32 s13, v252, 5
	v_readlane_b32 s14, v252, 6
	v_readlane_b32 s15, v252, 7
	v_readlane_b32 s16, v252, 8
	v_readlane_b32 s17, v252, 9
	v_readlane_b32 s18, v252, 10
	v_readlane_b32 s19, v252, 11
	v_readlane_b32 s22, v252, 14
	v_readlane_b32 s23, v252, 15
	v_readlane_b32 s24, v252, 16
	v_readlane_b32 s25, v252, 17
	v_readlane_b32 s26, v252, 18
	v_readlane_b32 s27, v252, 19
	s_waitcnt vmcnt(0)
	s_branch .LBB0_105

.LBB0_105:
	s_add_i32 s3, s4, s92
	s_cmpk_gt_i32 s3, 0x3ff
	s_cselect_b64 s[0:1], -1, 0
	s_and_b64 vcc, exec, s[0:1]
	s_waitcnt vmcnt(1)
	ds_write2_b32 v16, v0, v1 offset1:1
	ds_write2_b32 v16, v2, v3 offset0:2 offset1:3
	s_waitcnt vmcnt(1)
	ds_write2_b32 v17, v4, v5 offset1:1
	ds_write2_b32 v17, v6, v7 offset0:2 offset1:3
	s_cbranch_vccnz .LBB0_104
	s_ashr_i32 s5, s3, 31
	s_lshr_b32 s5, s5, 23
	s_add_i32 s5, s3, s5
	s_ashr_i32 s6, s5, 9
	s_and_b32 s5, s5, 0xfe00
	s_sub_i32 s5, s3, s5
	s_sext_i32_i16 s7, s5
	s_bfe_u32 s7, s7, 0x4001b
	s_add_i32 s7, s5, s7
	s_sext_i32_i16 s12, s7
	s_and_b32 s7, s7, 0xfff0
	s_sub_i32 s5, s5, s7
	s_ashr_i32 s7, s6, 31
	v_readlane_b32 s16, v252, 4
	s_lshl_b64 s[6:7], s[6:7], 23
	v_readlane_b32 s24, v252, 12
	v_readlane_b32 s25, v252, 13
	s_add_u32 s13, s24, s6
	s_sext_i32_i16 s5, s5
	s_addc_u32 s14, s25, s7
	s_lshl_b32 s6, s12, 2
	s_and_b32 s12, s6, 0xffffffc0
	s_lshl_b32 s6, s5, 6
	s_ashr_i32 s7, s6, 31
	s_lshl_b64 s[6:7], s[6:7], 2
	s_add_u32 s6, s13, s6
	v_add_u32_e32 v2, s12, v12
	s_addc_u32 s7, s14, s7
	v_mov_b32_e32 v11, v9
	v_ashrrev_i32_e32 v3, 31, v2
	v_lshl_add_u64 v[0:1], s[6:7], 0, v[10:11]
	v_lshlrev_b64 v[2:3], 12, v[2:3]
	v_lshl_add_u64 v[18:19], v[0:1], 0, v[2:3]
	v_add_u32_e32 v2, s12, v13
	v_ashrrev_i32_e32 v3, 31, v2
	v_lshlrev_b64 v[2:3], 12, v[2:3]
	v_lshl_add_u64 v[20:21], v[0:1], 0, v[2:3]
	global_load_dwordx4 v[0:3], v[18:19], off nt
	global_load_dwordx4 v[4:7], v[20:21], off nt
	v_readlane_b32 s17, v252, 5
	v_readlane_b32 s18, v252, 6
	v_readlane_b32 s19, v252, 7
	v_readlane_b32 s20, v252, 8
	v_readlane_b32 s21, v252, 9
	v_readlane_b32 s22, v252, 10
	v_readlane_b32 s23, v252, 11
	v_readlane_b32 s26, v252, 14
	v_readlane_b32 s27, v252, 15
	v_readlane_b32 s28, v252, 16
	v_readlane_b32 s29, v252, 17
	v_readlane_b32 s30, v252, 18
	v_readlane_b32 s31, v252, 19
	s_branch .LBB0_104
.LBB0_107:
	s_add_u32 s0, s42, 0xc000000
	s_addc_u32 s1, s43, 0
	v_writelane_b32 v252, s0, 22
	v_mov_b32_e32 v10, v170
	s_cmpk_gt_i32 s85, 0x5ff
	v_writelane_b32 v252, s1, 23
	s_cbranch_scc1 .LBB0_112
	s_mul_hi_i32 s0, s85, 0x2aaaaaab
	s_lshr_b32 s1, s0, 31
	s_lshr_b32 s0, s0, 8
	s_add_i32 s0, s0, s1
	s_mulk_i32 s0, 0x600
	s_sub_i32 s0, s85, s0
	s_mul_i32 s1, s0, 0x2aab
	s_lshr_b32 s3, s1, 31
	s_ashr_i32 s1, s1, 20
	s_add_i32 s1, s1, s3
	s_mul_i32 s3, s1, 0x60
	s_sub_i32 s0, s0, s3
	s_sext_i32_i16 s0, s0
	s_lshl_b32 s0, s0, 6
	s_lshl_b32 s4, s1, 6
	s_ashr_i32 s1, s0, 31
	v_readlane_b32 s12, v252, 4
	s_lshl_b64 s[0:1], s[0:1], 2
	v_readlane_b32 s22, v252, 14
	v_readlane_b32 s23, v252, 15
	s_add_u32 s0, s22, s0
	s_waitcnt vmcnt(2)
	v_lshlrev_b32_e32 v0, 4, v10
	s_addc_u32 s1, s23, s1
	v_and_b32_e32 v8, 0xf0, v0
	v_mov_b32_e32 v9, 0
	v_ashrrev_i32_e32 v12, 4, v10
	v_lshl_add_u64 v[0:1], s[0:1], 0, v[8:9]
	v_add_u32_e32 v2, s4, v12
	s_movk_i32 s3, 0x6000
	v_mad_i64_i32 v[14:15], s[0:1], v2, s3, v[0:1]
	v_add_u32_e32 v2, 0x200, v10
	v_ashrrev_i32_e32 v13, 4, v2
	v_add_u32_e32 v2, s4, v13
	v_mad_i64_i32 v[16:17], s[0:1], v2, s3, v[0:1]
	global_load_dwordx4 v[0:3], v[14:15], off nt
	global_load_dwordx4 v[4:7], v[16:17], off nt
	v_ashrrev_i32_e32 v14, 3, v10
	v_lshlrev_b32_e32 v10, 3, v10
	v_and_b32_e32 v18, 56, v10
	s_movk_i32 s0, 0x104
	v_mul_u32_u24_e32 v10, 0x104, v18
	v_lshlrev_b32_e32 v11, 2, v14
	v_add_u32_e32 v17, 0, v8
	v_add3_u32 v15, 0, v10, v11
	v_mul_lo_u32 v16, v12, s0
	v_mul_lo_u32 v19, v13, s0
	v_lshl_add_u64 v[10:11], s[22:23], 0, v[8:9]
	v_add_u32_e32 v16, v17, v16
	v_add_u32_e32 v17, v17, v19
	v_lshlrev_b32_e32 v8, 1, v18
	v_add_u32_e32 v18, 0x400, v15
	s_mov_b32 s5, s85
	v_readlane_b32 s13, v252, 5
	v_readlane_b32 s14, v252, 6
	v_readlane_b32 s15, v252, 7
	v_readlane_b32 s16, v252, 8
	v_readlane_b32 s17, v252, 9
	v_readlane_b32 s18, v252, 10
	v_readlane_b32 s19, v252, 11
	v_readlane_b32 s20, v252, 12
	v_readlane_b32 s21, v252, 13
	v_readlane_b32 s24, v252, 16
	v_readlane_b32 s25, v252, 17
	v_readlane_b32 s26, v252, 18
	v_readlane_b32 s27, v252, 19
	s_waitcnt vmcnt(0)
	s_branch .LBB0_110

.LBB0_110:
	s_add_i32 s4, s5, s92
	s_cmpk_gt_i32 s4, 0x5ff
	s_cselect_b64 s[0:1], -1, 0
	s_and_b64 vcc, exec, s[0:1]
	s_waitcnt vmcnt(1)
	ds_write2_b32 v16, v0, v1 offset1:1
	ds_write2_b32 v16, v2, v3 offset0:2 offset1:3
	s_waitcnt vmcnt(1)
	ds_write2_b32 v17, v4, v5 offset1:1
	ds_write2_b32 v17, v6, v7 offset0:2 offset1:3
	s_cbranch_vccnz .LBB0_109
	s_mul_hi_i32 s6, s4, 0x2aaaaaab
	s_lshr_b32 s7, s6, 31
	s_lshr_b32 s6, s6, 8
	s_add_i32 s6, s6, s7
	s_mulk_i32 s6, 0x600
	s_sub_i32 s6, s4, s6
	s_sext_i32_i16 s7, s6
	s_mulk_i32 s7, 0x2aab
	s_lshr_b32 s12, s7, 31
	s_ashr_i32 s7, s7, 20
	s_add_i32 s7, s7, s12
	s_mul_i32 s12, s7, 0x60
	s_sub_i32 s6, s6, s12
	s_sext_i32_i16 s6, s6
	s_lshl_b32 s6, s6, 6
	s_lshl_b32 s12, s7, 6
	s_ashr_i32 s7, s6, 31
	v_lshl_add_u64 v[0:1], s[6:7], 2, v[10:11]
	v_add_u32_e32 v2, s12, v12
	v_mad_i64_i32 v[20:21], s[6:7], v2, s3, v[0:1]
	v_add_u32_e32 v2, s12, v13
	v_mad_i64_i32 v[22:23], s[6:7], v2, s3, v[0:1]
	global_load_dwordx4 v[0:3], v[20:21], off nt
	global_load_dwordx4 v[4:7], v[22:23], off nt
	s_branch .LBB0_109
.LBB0_112:
	s_add_u32 s0, s42, 0xcc00000
	v_writelane_b32 v252, s0, 24
	s_addc_u32 s0, s43, 0
	v_writelane_b32 v252, s0, 25
	v_mov_b32_e32 v10, v170
	s_cmpk_gt_i32 s85, 0x7ff
	s_cbranch_scc1 .LBB0_117
	s_ashr_i32 s0, s85, 31
	s_lshr_b32 s0, s0, 22
	s_add_i32 s1, s85, s0
	s_ashr_i32 s0, s1, 10
	s_and_b32 s1, s1, 0xfc00
	s_sub_i32 s1, s85, s1
	s_sext_i32_i16 s3, s1
	s_bfe_u32 s3, s3, 0x60019
	s_add_i32 s3, s1, s3
	s_sext_i32_i16 s4, s3
	s_and_b32 s3, s3, 0xffc0
	s_sub_i32 s1, s1, s3
	s_sext_i32_i16 s3, s1
	s_ashr_i32 s1, s0, 31
	v_readlane_b32 s12, v252, 4
	s_lshl_b64 s[0:1], s[0:1], 24
	v_readlane_b32 s24, v252, 16
	v_readlane_b32 s25, v252, 17
	s_add_u32 s5, s24, s0
	s_addc_u32 s6, s25, s1
	s_lshl_b32 s0, s3, 6
	s_ashr_i32 s1, s0, 31
	s_andn2_b32 s4, s4, 63
	s_lshl_b64 s[0:1], s[0:1], 2
	s_waitcnt vmcnt(2)
	v_lshlrev_b32_e32 v0, 2, v10
	v_ashrrev_i32_e32 v12, 4, v10
	s_add_u32 s0, s5, s0
	v_and_b32_e32 v18, 60, v0
	v_add_u32_e32 v2, s4, v12
	s_addc_u32 s1, s6, s1
	v_mov_b32_e32 v9, 0
	v_lshlrev_b32_e32 v8, 2, v18
	v_ashrrev_i32_e32 v3, 31, v2
	v_lshl_add_u64 v[0:1], s[0:1], 0, v[8:9]
	v_lshlrev_b64 v[2:3], 14, v[2:3]
	v_lshl_add_u64 v[14:15], v[0:1], 0, v[2:3]
	v_add_u32_e32 v2, 0x200, v10
	v_ashrrev_i32_e32 v13, 4, v2
	v_add_u32_e32 v2, s4, v13
	v_ashrrev_i32_e32 v3, 31, v2
	v_lshlrev_b64 v[2:3], 14, v[2:3]
	v_lshl_add_u64 v[16:17], v[0:1], 0, v[2:3]
	global_load_dwordx4 v[0:3], v[14:15], off nt
	global_load_dwordx4 v[4:7], v[16:17], off nt
	v_add_u32_e32 v11, 0, v8
	v_lshlrev_b32_e32 v8, 3, v10
	v_ashrrev_i32_e32 v14, 3, v10
	v_and_b32_e32 v8, 56, v8
	s_movk_i32 s0, 0x104
	v_mul_u32_u24_e32 v10, 0x104, v8
	v_lshlrev_b32_e32 v15, 2, v14
	v_add3_u32 v15, 0, v10, v15
	v_mul_lo_u32 v10, v12, s0
	v_mul_lo_u32 v17, v13, s0
	v_add_u32_e32 v16, v11, v10
	v_add_u32_e32 v17, v11, v17
	v_lshlrev_b32_e32 v10, 2, v18
	v_lshlrev_b32_e32 v8, 1, v8
	s_mov_b32 s4, s85
	v_readlane_b32 s13, v252, 5
	v_readlane_b32 s14, v252, 6
	v_readlane_b32 s15, v252, 7
	v_readlane_b32 s16, v252, 8
	v_readlane_b32 s17, v252, 9
	v_readlane_b32 s18, v252, 10
	v_readlane_b32 s19, v252, 11
	v_readlane_b32 s20, v252, 12
	v_readlane_b32 s21, v252, 13
	v_readlane_b32 s22, v252, 14
	v_readlane_b32 s23, v252, 15
	v_readlane_b32 s26, v252, 18
	v_readlane_b32 s27, v252, 19
	s_waitcnt vmcnt(0)
	s_branch .LBB0_115

.LBB0_115:
	s_add_i32 s3, s4, s92
	s_cmpk_gt_i32 s3, 0x7ff
	s_cselect_b64 s[0:1], -1, 0
	s_and_b64 vcc, exec, s[0:1]
	s_waitcnt vmcnt(1)
	ds_write2_b32 v16, v0, v1 offset1:1
	ds_write2_b32 v16, v2, v3 offset0:2 offset1:3
	s_waitcnt vmcnt(1)
	ds_write2_b32 v17, v4, v5 offset1:1
	ds_write2_b32 v17, v6, v7 offset0:2 offset1:3
	s_cbranch_vccnz .LBB0_114
	s_ashr_i32 s5, s3, 31
	s_lshr_b32 s5, s5, 22
	s_add_i32 s5, s3, s5
	s_ashr_i32 s6, s5, 10
	s_and_b32 s5, s5, 0xfc00
	s_sub_i32 s5, s3, s5
	s_sext_i32_i16 s7, s5
	s_bfe_u32 s7, s7, 0x60019
	s_add_i32 s7, s5, s7
	s_sext_i32_i16 s12, s7
	s_and_b32 s7, s7, 0xffc0
	s_sub_i32 s5, s5, s7
	s_ashr_i32 s7, s6, 31
	v_readlane_b32 s16, v252, 4
	s_lshl_b64 s[6:7], s[6:7], 24
	v_readlane_b32 s28, v252, 16
	s_sext_i32_i16 s5, s5
	v_readlane_b32 s29, v252, 17
	s_add_u32 s13, s28, s6
	s_addc_u32 s14, s29, s7
	s_lshl_b32 s6, s5, 6
	s_ashr_i32 s7, s6, 31
	s_andn2_b32 s12, s12, 63
	s_lshl_b64 s[6:7], s[6:7], 2
	s_add_u32 s6, s13, s6
	v_add_u32_e32 v2, s12, v12
	s_addc_u32 s7, s14, s7
	v_mov_b32_e32 v11, v9
	v_ashrrev_i32_e32 v3, 31, v2
	v_lshl_add_u64 v[0:1], s[6:7], 0, v[10:11]
	v_lshlrev_b64 v[2:3], 14, v[2:3]
	v_lshl_add_u64 v[18:19], v[0:1], 0, v[2:3]
	v_add_u32_e32 v2, s12, v13
	v_ashrrev_i32_e32 v3, 31, v2
	v_lshlrev_b64 v[2:3], 14, v[2:3]
	v_lshl_add_u64 v[20:21], v[0:1], 0, v[2:3]
	global_load_dwordx4 v[0:3], v[18:19], off nt
	global_load_dwordx4 v[4:7], v[20:21], off nt
	v_readlane_b32 s17, v252, 5
	v_readlane_b32 s18, v252, 6
	v_readlane_b32 s19, v252, 7
	v_readlane_b32 s20, v252, 8
	v_readlane_b32 s21, v252, 9
	v_readlane_b32 s22, v252, 10
	v_readlane_b32 s23, v252, 11
	v_readlane_b32 s24, v252, 12
	v_readlane_b32 s25, v252, 13
	v_readlane_b32 s26, v252, 14
	v_readlane_b32 s27, v252, 15
	v_readlane_b32 s30, v252, 18
	v_readlane_b32 s31, v252, 19
	s_branch .LBB0_114

.LBB0_759:
	s_and_b64 vcc, exec, s[6:7]
	s_cbranch_vccz .LBB0_789
	v_readlane_b32 s0, v254, 54
	v_readlane_b32 s1, v254, 55
	v_mov_b32_e32 v0, v170
	s_and_b64 vcc, exec, s[0:1]
	s_cbranch_vccnz .LBB0_765
	v_lshlrev_b32_e32 v1, 2, v0
	v_and_b32_e32 v18, 60, v1
	v_readlane_b32 s0, v253, 45
	v_lshlrev_b32_e32 v2, 2, v18
	v_readlane_b32 s1, v253, 46
	v_add_u32_e32 v1, 0x200, v0
	v_ashrrev_i32_e32 v12, 4, v0
	v_lshl_add_u64 v[4:5], s[0:1], 0, v[2:3]
	v_readlane_b32 s0, v253, 44
	v_ashrrev_i32_e32 v13, 4, v1
	v_ashrrev_i32_e32 v14, 3, v0
	v_add_u32_e32 v6, s0, v12
	v_add_u32_e32 v8, s0, v13
	v_ashrrev_i32_e32 v7, 31, v6
	v_ashrrev_i32_e32 v9, 31, v8
	v_lshlrev_b64 v[6:7], 12, v[6:7]
	v_lshlrev_b64 v[8:9], 12, v[8:9]
	v_lshl_add_u64 v[6:7], v[4:5], 0, v[6:7]
	v_lshl_add_u64 v[8:9], v[4:5], 0, v[8:9]
	global_load_dwordx4 v[4:7], v[6:7], off nt
	s_nop 0
	global_load_dwordx4 v[8:11], v[8:9], off nt
	v_lshlrev_b32_e32 v0, 3, v0
	v_add_u32_e32 v1, 0, v2
	v_and_b32_e32 v2, 56, v0
	v_mul_u32_u24_e32 v0, 0x104, v2
	v_lshlrev_b32_e32 v15, 2, v14
	s_movk_i32 s0, 0x104
	v_add3_u32 v15, 0, v0, v15
	v_mul_lo_u32 v0, v12, s0
	v_mul_lo_u32 v17, v13, s0
	v_add_u32_e32 v16, v1, v0
	v_add_u32_e32 v17, v1, v17
	v_lshlrev_b32_e32 v0, 2, v18
	v_lshlrev_b32_e32 v2, 1, v2
	s_waitcnt vmcnt(0)
	s_branch .LBB0_763

.LBB0_763:
	s_add_i32 s0, s85, s92
	s_cmpk_gt_i32 s0, 0x1ff
	s_cselect_b64 s[4:5], -1, 0
	s_and_b64 vcc, exec, s[4:5]
	s_waitcnt vmcnt(1)
	ds_write2_b32 v16, v4, v5 offset1:1
	ds_write2_b32 v16, v6, v7 offset0:2 offset1:3
	s_waitcnt vmcnt(1)
	ds_write2_b32 v17, v8, v9 offset1:1
	ds_write2_b32 v17, v10, v11 offset0:2 offset1:3
	s_cbranch_vccnz .LBB0_762
	s_ashr_i32 s2, s0, 31
	s_lshr_b32 s2, s2, 24
	s_add_i32 s3, s0, s2
	s_ashr_i32 s2, s3, 8
	s_and_b32 s3, s3, 0xff00
	s_sub_i32 s3, s0, s3
	s_sext_i32_i16 s6, s3
	s_bfe_u32 s6, s6, 0x4001b
	s_add_i32 s6, s3, s6
	s_sext_i32_i16 s7, s6
	s_and_b32 s6, s6, 0xfff0
	s_sub_i32 s3, s3, s6
	v_readlane_b32 s44, v252, 4
	s_sext_i32_i16 s6, s3
	s_ashr_i32 s3, s2, 31
	v_readlane_b32 s58, v252, 18
	v_readlane_b32 s59, v252, 19
	s_lshl_b64 s[2:3], s[2:3], 22
	s_mov_b64 s[14:15], s[58:59]
	s_add_u32 s8, s14, s2
	s_addc_u32 s9, s15, s3
	s_lshl_b32 s2, s7, 2
	s_and_b32 s7, s2, 0xffffffc0
	s_lshl_b32 s2, s6, 6
	s_ashr_i32 s3, s2, 31
	s_lshl_b64 s[2:3], s[2:3], 2
	s_add_u32 s2, s8, s2
	v_add_u32_e32 v6, s7, v12
	v_add_u32_e32 v8, s7, v13
	s_addc_u32 s3, s9, s3
	v_mov_b32_e32 v1, v3
	v_ashrrev_i32_e32 v7, 31, v6
	v_ashrrev_i32_e32 v9, 31, v8
	v_lshl_add_u64 v[4:5], s[2:3], 0, v[0:1]
	v_lshlrev_b64 v[6:7], 12, v[6:7]
	v_lshlrev_b64 v[8:9], 12, v[8:9]
	v_lshl_add_u64 v[6:7], v[4:5], 0, v[6:7]
	v_lshl_add_u64 v[8:9], v[4:5], 0, v[8:9]
	global_load_dwordx4 v[4:7], v[6:7], off nt
	s_nop 0
	global_load_dwordx4 v[8:11], v[8:9], off nt
	v_readlane_b32 s45, v252, 5
	v_readlane_b32 s46, v252, 6
	v_readlane_b32 s47, v252, 7
	v_readlane_b32 s48, v252, 8
	v_readlane_b32 s49, v252, 9
	v_readlane_b32 s50, v252, 10
	v_readlane_b32 s51, v252, 11
	v_readlane_b32 s52, v252, 12
	v_readlane_b32 s53, v252, 13
	v_readlane_b32 s54, v252, 14
	v_readlane_b32 s55, v252, 15
	v_readlane_b32 s56, v252, 16
	v_readlane_b32 s57, v252, 17
	s_branch .LBB0_762
